# attention prologue: rope-Q loads issued together; ctx_combine vector loads prefetched; zt loads issued together; FFT table staging loads issued together
# speedup vs baseline: 1.0256x; 1.0007x over previous
.LBB0_821:
	s_cmpk_gt_i32 s49, 0xff
	s_mov_b64 s[0:1], -1
	s_cbranch_scc0 .LBB0_853
	s_add_i32 s0, s49, 0xffffff00
	s_lshr_b32 s68, s0, 2
	s_and_b32 s2, s49, 3
	s_lshl_b64 s[0:1], s[68:69], 8
	s_add_u32 s44, s0, 0x4000
	s_addc_u32 s45, s1, 0
	s_mul_i32 s0, s45, 0x600
	s_mul_hi_u32 s10, s44, 0x600
	s_add_i32 s10, s10, s0
	s_mul_i32 s11, s44, 0x600
	s_add_u32 s0, s84, s11
	s_addc_u32 s1, s85, s10
	s_mul_i32 s4, s2, 0x180
	s_add_u32 s0, s0, s4
	s_addc_u32 s1, s1, 0
	v_readlane_b32 s8, v251, 48
	v_readlane_b32 s9, v251, 49
	s_add_u32 s8, s8, s4
	s_addc_u32 s9, s9, 0
	s_lshl_b32 s4, s2, 8
	v_readlane_b32 s12, v253, 7
	v_mov_b32_e32 v166, v0
	v_readlane_b32 s13, v253, 8
	s_add_u32 s4, s12, s4
	s_addc_u32 s7, s13, 0
	v_ashrrev_i32_e32 v157, 6, v166
	v_and_b32_e32 v168, 31, v166
	v_and_b32_e32 v2, 0x3fffffc0, v166
	s_add_i32 s12, 0, 0x14000
	v_lshlrev_b32_e32 v156, 5, v157
	v_bfe_u32 v169, v166, 5, 1
	v_lshl_add_u32 v48, v2, 2, s12
	v_or_b32_e32 v4, v156, v168
	s_waitcnt lgkmcnt(0)
	v_mov_b64_e32 v[2:3], s[0:1]
	s_movk_i32 s12, 0x600
	v_mad_i64_i32 v[2:3], s[0:1], v4, s12, v[2:3]
	v_lshlrev_b32_e32 v46, 4, v169
	v_mov_b32_e32 v47, v99
	v_lshl_add_u64 v[8:9], v[2:3], 0, v[46:47]
	global_load_dwordx4 v[128:131], v[8:9], off
	global_load_dwordx4 v[124:127], v[8:9], off offset:32
	global_load_dwordx4 v[120:123], v[8:9], off offset:64
	global_load_dwordx4 v[116:119], v[8:9], off offset:96
	global_load_dwordx4 v[112:115], v[8:9], off offset:128
	global_load_dwordx4 v[108:111], v[8:9], off offset:160
	global_load_dwordx4 v[104:107], v[8:9], off offset:192
	global_load_dwordx4 v[100:103], v[8:9], off offset:224
	global_load_dwordx4 v[4:7], v[8:9], off offset:256
	global_load_dwordx4 v[132:135], v[8:9], off offset:288
	global_load_dwordx4 v[136:139], v[8:9], off offset:320
	global_load_dwordx4 v[140:143], v[8:9], off offset:352
	v_lshlrev_b32_e32 v2, 12, v157
	s_add_i32 s0, 0, 0x14800
	v_lshlrev_b32_e32 v3, 7, v168
	v_add3_u32 v35, s0, v2, v3
	v_bitop3_b32 v3, v169, v166, 7 bitop3:0x78
	v_lshl_add_u32 v3, v3, 4, v35
	v_lshlrev_b32_e32 v2, 4, v166
	v_and_b32_e32 v34, 0x70, v2
	s_movk_i32 s0, 0x60
	s_movk_i32 s16, 0x180
	v_and_b32_e32 v167, 63, v166
	s_cmp_lg_u32 0, -1
	v_mul_u32_u24_e32 v39, 0x180, v168
	v_or_b32_e32 v36, 32, v46
	v_bitop3_b32 v40, v36, v39, v34 bitop3:0xde
	v_add_u32_e32 v178, 0, v40
	v_or_b32_e32 v37, 64, v46
	v_or_b32_e32 v38, 0x60, v46
	v_cmp_gt_u32_e64 s[40:41], 32, v167
	v_lshl_add_u32 v175, v168, 2, v48
	v_add_u32_e32 v174, v48, v46
	s_waitcnt vmcnt(0)
	ds_write_b128 v3, v[4:7]
	v_bitop3_b32 v3, v46, v34, 32 bitop3:0x36
	v_add_u32_e32 v172, v35, v3
	v_bitop3_b32 v3, v46, v34, 64 bitop3:0x36
	v_add_u32_e32 v173, v35, v3
	v_bitop3_b32 v3, v46, v34, s0 bitop3:0x36
	v_add_u32_e32 v171, v35, v3
	v_ashrrev_i32_e32 v3, 4, v166
	s_mov_b32 s0, 0x2aaaaaab
	ds_write_b128 v172, v[132:135]
	ds_write_b128 v173, v[136:139]
	v_and_b32_e32 v8, 3, v3
	ds_write_b128 v171, v[140:143]
	v_and_b32_e32 v6, 0xfffff0, v3
	v_lshlrev_b32_e32 v7, 1, v3
	v_and_or_b32 v6, v7, 8, v6
	v_lshrrev_b32_e32 v7, 1, v3
	v_and_or_b32 v7, v7, 4, v8
	v_add_u32_e32 v8, 32, v3
	v_and_b32_e32 v9, 0xfffff0, v8
	v_lshlrev_b32_e32 v8, 1, v8
	v_lshlrev_b32_e32 v4, 3, v166
	v_and_or_b32 v8, v8, 8, v9
	v_and_b32_e32 v5, 0x78, v4
	v_lshrrev_b32_e32 v6, 1, v6
	v_bfe_u32 v4, v4, 5, 2
	v_lshrrev_b32_e32 v8, 1, v8
	v_or_b32_e32 v6, v6, v4
	v_or_b32_e32 v4, v8, v4
	v_mul_hi_i32 v8, v166, s0
	v_lshrrev_b32_e32 v9, 31, v8
	v_ashrrev_i32_e32 v8, 2, v8
	v_add_u32_e32 v8, v8, v9
	v_mul_lo_u32 v9, v8, 24
	v_sub_u32_e32 v9, v166, v9
	v_mul_lo_u32 v10, v8, s12
	v_lshl_add_u32 v158, v9, 4, v10
	v_mul_lo_u32 v10, v8, s16
	v_bitop3_b32 v8, v8, v9, 7 bitop3:0x6c
	v_lshl_add_u32 v24, v8, 4, v10
	v_add_u32_e32 v8, 0x200, v166
	v_mul_hi_i32 v9, v8, s0
	v_lshrrev_b32_e32 v10, 31, v9
	v_ashrrev_i32_e32 v9, 2, v9
	v_add_u32_e32 v9, v9, v10
	v_mul_lo_u32 v10, v9, 24
	v_sub_u32_e32 v8, v8, v10
	v_mul_lo_u32 v10, v9, s12
	v_lshl_add_u32 v160, v8, 4, v10
	v_mul_lo_u32 v10, v9, s16
	v_bitop3_b32 v8, v9, v8, 7 bitop3:0x6c
	v_lshl_add_u32 v25, v8, 4, v10
	v_add_u32_e32 v8, 0x400, v166
	v_mul_hi_i32 v9, v8, s0
	v_lshrrev_b32_e32 v10, 31, v9
	v_ashrrev_i32_e32 v9, 2, v9
	v_add_u32_e32 v9, v9, v10
	v_mul_lo_u32 v10, v9, 24
	v_sub_u32_e32 v8, v8, v10
	v_mul_lo_u32 v10, v9, s12
	v_lshlrev_b32_e32 v5, 1, v5
	v_lshl_add_u32 v162, v8, 4, v10
	v_mul_lo_u32 v10, v9, s16
	v_bitop3_b32 v8, v9, v8, 7 bitop3:0x6c
	v_lshlrev_b32_e32 v7, 6, v7
	v_lshlrev_b32_e32 v4, 9, v4
	v_lshl_add_u32 v26, v8, 4, v10
	v_and_b32_e32 v8, 48, v5
	v_or3_b32 v28, v4, v7, v8
	v_lshl_or_b32 v98, v3, 10, v5
	v_lshlrev_b32_e32 v3, 3, v167
	v_and_b32_e32 v4, 0xc0, v2
	v_lshlrev_b32_e32 v5, 1, v166
	v_and_or_b32 v4, v3, 24, v4
	v_and_b32_e32 v5, 32, v5
	v_and_b32_e32 v3, 0x100, v3
	v_or3_b32 v152, v4, v5, v3
	s_cselect_b32 s0, 0, 0
	v_add_u32_e32 v170, s0, v152
	s_lshl_b64 s[0:1], s[44:45], 10
	s_add_u32 s12, s4, s0
	s_addc_u32 s13, s7, s1
	v_lshlrev_b32_e32 v6, 9, v6
	s_add_u32 s14, s8, s11
	v_or3_b32 v27, v6, v7, v8
	v_add_u32_e32 v164, 0x8000, v98
	s_addc_u32 s15, s9, s10
	global_load_dwordx4 v[4:7], v98, s[12:13]
	global_load_dwordx4 v[8:11], v164, s[12:13]
	global_load_dwordx4 v[12:15], v158, s[14:15]
	global_load_dwordx4 v[16:19], v160, s[14:15]
	global_load_dwordx4 v[20:23], v162, s[14:15]
	s_movk_i32 s10, 0x70
	v_bitop3_b32 v45, v46, v2, s10 bitop3:0x78
	v_bitop3_b32 v2, v46, v39, v34 bitop3:0xde
	v_add_u32_e32 v214, 0, v27
	v_add_u32_e32 v215, 0, v28
	v_add_u32_e32 v216, 0, v24
	v_add_u32_e32 v217, 0, v25
	v_add_u32_e32 v218, 0, v26
	v_mov_b32_e32 v3, 0x3000
	v_add_u32_e32 v176, 0, v2
	s_waitcnt vmcnt(0)
	v_mad_u32_u24 v44, v168, s16, v3
	v_bitop3_b32 v179, v36, v44, v34 bitop3:0xde
	v_bitop3_b32 v36, v37, v39, v34 bitop3:0xde
	v_add_u32_e32 v180, 0, v36
	v_bitop3_b32 v36, v38, v39, v34 bitop3:0xde
	v_add_u32_e32 v182, 0, v36
	v_bitop3_b32 v181, v37, v44, v34 bitop3:0xde
	v_bitop3_b32 v183, v38, v44, v34 bitop3:0xde
	s_movk_i32 s10, 0x80
	v_add_u32_e32 v194, v35, v45
	v_bitop3_b32 v177, v46, v44, v34 bitop3:0xde
	s_mul_i32 s15, s68, 0x60000
	s_mul_hi_u32 s14, s68, 0x60000
	s_waitcnt vmcnt(4)
	ds_write_b128 v214, v[4:7]
	s_waitcnt vmcnt(3)
	ds_write_b128 v215, v[8:11]
	s_waitcnt vmcnt(2)
	ds_write_b128 v216, v[12:15] offset:32768
	s_waitcnt vmcnt(1)
	ds_write_b128 v217, v[16:19] offset:32768
	s_waitcnt vmcnt(0)
	ds_write_b128 v218, v[20:23] offset:32768
	s_waitcnt lgkmcnt(0)
	s_barrier
	ds_read_b128 v[2:5], v176 offset:32768
	ds_read_b128 v[6:9], v176 offset:45056
	ds_read_b128 v[40:43], v178 offset:32768
	ds_read_b128 v[50:53], v178 offset:45056
	s_waitcnt lgkmcnt(3)
	v_mfma_f32_32x32x16_bf16 v[18:33], v[2:5], v[128:131], 0
	ds_read_b128 v[36:39], v182 offset:45056
	s_waitcnt lgkmcnt(3)
	v_mfma_f32_32x32x16_bf16 v[2:17], v[6:9], v[128:131], 0
	s_waitcnt lgkmcnt(2)
	v_mfma_f32_32x32x16_bf16 v[18:33], v[40:43], v[124:127], v[18:33]
	ds_read_b128 v[40:43], v180 offset:32768
	s_waitcnt lgkmcnt(2)
	v_mfma_f32_32x32x16_bf16 v[2:17], v[50:53], v[124:127], v[2:17]
	ds_read_b128 v[50:53], v180 offset:45056
	s_waitcnt lgkmcnt(1)
	v_mfma_f32_32x32x16_bf16 v[18:33], v[40:43], v[120:123], v[18:33]
	ds_read_b128 v[40:43], v182 offset:32768
	s_waitcnt lgkmcnt(1)
	v_mfma_f32_32x32x16_bf16 v[2:17], v[50:53], v[120:123], v[2:17]
	ds_read_b128 v[50:53], v194
	s_waitcnt lgkmcnt(1)
	v_mfma_f32_32x32x16_bf16 v[18:33], v[40:43], v[116:119], v[18:33]
	v_bitop3_b32 v40, v46, v34, s10 bitop3:0x36
	v_add_u32_e32 v185, v40, v44
	s_movk_i32 s10, 0xa0
	v_mfma_f32_32x32x16_bf16 v[2:17], v[36:39], v[116:119], v[2:17]
	v_mad_u32_u24 v36, v168, s16, v40
	v_add_u32_e32 v184, 0, v36
	ds_read_b128 v[36:39], v184 offset:32768
	ds_read_b128 v[40:43], v184 offset:45056
	s_waitcnt lgkmcnt(0)
	v_mfma_f32_32x32x16_bf16 v[2:17], v[40:43], v[112:115], v[2:17]
	v_bitop3_b32 v40, v46, v34, s10 bitop3:0x36
	v_add_u32_e32 v187, v40, v44
	s_movk_i32 s10, 0xc0
	v_mfma_f32_32x32x16_bf16 v[18:33], v[36:39], v[112:115], v[18:33]
	v_mad_u32_u24 v36, v168, s16, v40
	v_add_u32_e32 v186, 0, v36
	ds_read_b128 v[36:39], v186 offset:32768
	ds_read_b128 v[40:43], v186 offset:45056
	s_waitcnt lgkmcnt(0)
	v_mfma_f32_32x32x16_bf16 v[2:17], v[40:43], v[108:111], v[2:17]
	v_bitop3_b32 v40, v46, v34, s10 bitop3:0x36
	v_add_u32_e32 v189, v40, v44
	s_movk_i32 s10, 0xe0
	v_mfma_f32_32x32x16_bf16 v[18:33], v[36:39], v[108:111], v[18:33]
	v_mad_u32_u24 v36, v168, s16, v40
	v_add_u32_e32 v188, 0, v36
	ds_read_b128 v[36:39], v188 offset:32768
	ds_read_b128 v[40:43], v188 offset:45056
	s_waitcnt lgkmcnt(0)
	v_mfma_f32_32x32x16_bf16 v[2:17], v[40:43], v[104:107], v[2:17]
	v_bitop3_b32 v40, v46, v34, s10 bitop3:0x36
	v_add_u32_e32 v191, v40, v44
	s_movk_i32 s10, 0x120
	v_bitop3_b32 v35, v46, v34, s10 bitop3:0x36
	s_movk_i32 s10, 0x140
	v_add_u32_e32 v196, v35, v44
	v_mfma_f32_32x32x16_bf16 v[18:33], v[36:39], v[104:107], v[18:33]
	v_mad_u32_u24 v36, v168, s16, v40
	v_add_u32_e32 v190, 0, v36
	ds_read_b128 v[36:39], v190 offset:32768
	ds_read_b128 v[40:43], v190 offset:45056
	s_waitcnt lgkmcnt(0)
	v_mfma_f32_32x32x16_bf16 v[2:17], v[40:43], v[100:103], v[2:17]
	v_bitop3_b32 v40, v46, v34, s82 bitop3:0x36
	v_add_u32_e32 v193, v40, v44
	v_mfma_f32_32x32x16_bf16 v[18:33], v[36:39], v[100:103], v[18:33]
	v_mad_u32_u24 v36, v168, s16, v40
	v_add_u32_e32 v192, 0, v36
	ds_read_b128 v[36:39], v192 offset:32768
	ds_read_b128 v[40:43], v192 offset:45056
	s_waitcnt lgkmcnt(1)
	v_mfma_f32_32x32x16_bf16 v[18:33], v[36:39], v[50:53], v[18:33]
	v_mad_u32_u24 v36, v168, s16, v35
	v_add_u32_e32 v195, 0, v36
	ds_read_b128 v[36:39], v195 offset:32768
	v_bitop3_b32 v35, v46, v34, s10 bitop3:0x36
	s_movk_i32 s10, 0x160
	v_bitop3_b32 v34, v46, v34, s10 bitop3:0x36
	v_add_u32_e32 v198, v35, v44
	s_waitcnt lgkmcnt(1)
	v_mfma_f32_32x32x16_bf16 v[2:17], v[40:43], v[50:53], v[2:17]
	ds_read_b128 v[40:43], v195 offset:45056
	ds_read_b128 v[50:53], v172
	v_add_u32_e32 v213, v34, v44
	s_waitcnt lgkmcnt(0)
	v_mfma_f32_32x32x16_bf16 v[18:33], v[36:39], v[50:53], v[18:33]
	v_mad_u32_u24 v36, v168, s16, v35
	v_add_u32_e32 v197, 0, v36
	ds_read_b128 v[36:39], v197 offset:32768
	v_mad_u32_u24 v35, v168, s16, v34
	v_add_u32_e32 v199, 0, v35
	v_mfma_f32_32x32x16_bf16 v[2:17], v[40:43], v[50:53], v[2:17]
	ds_read_b128 v[40:43], v197 offset:45056
	ds_read_b128 v[50:53], v173
	s_waitcnt lgkmcnt(0)
	v_mfma_f32_32x32x16_bf16 v[18:33], v[36:39], v[50:53], v[18:33]
	v_mfma_f32_32x32x16_bf16 v[2:17], v[40:43], v[50:53], v[2:17]
	ds_read_b128 v[38:41], v199 offset:32768
	ds_read_b128 v[34:37], v199 offset:45056
	ds_read_b128 v[42:45], v171
	s_waitcnt lgkmcnt(0)
	v_mfma_f32_32x32x16_bf16 v[18:33], v[38:41], v[42:45], v[18:33]
	v_mfma_f32_32x32x16_bf16 v[2:17], v[34:37], v[42:45], v[2:17]
	s_nop 10
	v_max_f32_e32 v34, v19, v19
	v_max_f32_e32 v35, v18, v18
	v_max_f32_e32 v34, v35, v34
	v_max3_f32 v34, v34, v20, v21
	v_max3_f32 v34, v34, v22, v23
	v_max3_f32 v34, v34, v24, v25
	v_max3_f32 v34, v34, v26, v27
	v_max3_f32 v34, v34, v28, v29
	v_max3_f32 v34, v34, v30, v31
	v_max3_f32 v34, v34, v32, v33
	v_max3_f32 v34, v34, v2, v3
	v_max3_f32 v34, v34, v4, v5
	v_max3_f32 v34, v34, v6, v7
	v_max3_f32 v34, v34, v8, v9
	v_max3_f32 v34, v34, v10, v11
	v_max3_f32 v34, v34, v12, v13
	v_max3_f32 v34, v34, v14, v15
	v_max3_f32 v34, v34, v16, v17
	v_mov_b32_e32 v35, v34
	s_nop 1
	v_permlane32_swap_b32_e32 v34, v35
	v_max_f32_e32 v35, v35, v35
	v_max_f32_e32 v34, v34, v34
	v_max_f32_e32 v34, v34, v35
	v_add_f32_e32 v35, 0x7149f2ca, v34
	v_cmp_ge_f32_e32 vcc, s5, v35
	s_cmp_eq_u64 vcc, exec
	s_cselect_b64 s[38:39], -1, 0
	s_lshl_b64 s[10:11], s[68:69], 18
	s_add_u32 s10, s4, s10
	s_addc_u32 s11, s7, s11
	s_add_u32 s12, s10, 0x1010000
	v_max_f32_e32 v154, 0xf149f2ca, v34
	v_mov_b32_e32 v34, 0xf149f2ca
	s_addc_u32 s13, s11, 0
	v_cndmask_b32_e64 v153, v154, v34, s[38:39]
	s_add_u32 s8, s8, s15
	v_mul_f32_e32 v38, 0xbdd53b94, v153
	s_addc_u32 s9, s9, s14
	v_fmamk_f32 v18, v18, 0x3dd53b94, v38
	v_fmamk_f32 v19, v19, 0x3dd53b94, v38
	v_fmamk_f32 v20, v20, 0x3dd53b94, v38
	v_fmamk_f32 v21, v21, 0x3dd53b94, v38
	s_add_u32 s14, s8, 0x1818000
	v_fmamk_f32 v22, v22, 0x3dd53b94, v38
	v_fmamk_f32 v23, v23, 0x3dd53b94, v38
	v_fmamk_f32 v24, v24, 0x3dd53b94, v38
	v_fmamk_f32 v25, v25, 0x3dd53b94, v38
	v_fmamk_f32 v26, v26, 0x3dd53b94, v38
	v_fmamk_f32 v27, v27, 0x3dd53b94, v38
	v_fmamk_f32 v28, v28, 0x3dd53b94, v38
	v_fmamk_f32 v29, v29, 0x3dd53b94, v38
	v_fmamk_f32 v56, v30, 0x3dd53b94, v38
	v_fmamk_f32 v57, v31, 0x3dd53b94, v38
	v_fmamk_f32 v58, v32, 0x3dd53b94, v38
	v_fmamk_f32 v59, v33, 0x3dd53b94, v38
	v_fmamk_f32 v51, v2, 0x3dd53b94, v38
	v_fmamk_f32 v52, v3, 0x3dd53b94, v38
	v_fmamk_f32 v53, v4, 0x3dd53b94, v38
	v_fmamk_f32 v54, v5, 0x3dd53b94, v38
	v_fmamk_f32 v55, v6, 0x3dd53b94, v38
	v_fmamk_f32 v42, v7, 0x3dd53b94, v38
	v_fmamk_f32 v43, v8, 0x3dd53b94, v38
	v_fmamk_f32 v44, v9, 0x3dd53b94, v38
	v_fmamk_f32 v45, v10, 0x3dd53b94, v38
	v_fmamk_f32 v47, v11, 0x3dd53b94, v38
	v_fmamk_f32 v49, v12, 0x3dd53b94, v38
	v_fmamk_f32 v50, v13, 0x3dd53b94, v38
	v_fmamk_f32 v39, v14, 0x3dd53b94, v38
	v_fmamk_f32 v40, v15, 0x3dd53b94, v38
	v_fmamk_f32 v41, v16, 0x3dd53b94, v38
	v_fmac_f32_e32 v38, 0x3dd53b94, v17
	v_exp_f32_e32 v31, v18
	v_exp_f32_e32 v33, v19
	v_exp_f32_e32 v34, v20
	v_exp_f32_e32 v35, v21
	s_addc_u32 s15, s9, 0
	global_load_dwordx4 v[2:5], v98, s[12:13]
	global_load_dwordx4 v[6:9], v164, s[12:13]
	global_load_dwordx4 v[10:13], v158, s[14:15]
	global_load_dwordx4 v[14:17], v160, s[14:15]
	global_load_dwordx4 v[18:21], v162, s[14:15]
	v_exp_f32_e32 v36, v22
	v_exp_f32_e32 v37, v23
	v_exp_f32_e32 v30, v24
	v_exp_f32_e32 v32, v25
	v_exp_f32_e32 v25, v26
	v_exp_f32_e32 v27, v27
	v_exp_f32_e32 v28, v28
	v_exp_f32_e32 v29, v29
	v_exp_f32_e32 v22, v56
	v_exp_f32_e32 v23, v57
	v_exp_f32_e32 v24, v58
	v_exp_f32_e32 v26, v59
	s_waitcnt vmcnt(0)
	s_add_i32 s12, 0, 0xe000
	s_waitcnt vmcnt(4)
	ds_write_b128 v214, v[2:5] offset:16384
	s_waitcnt vmcnt(3)
	ds_write_b128 v215, v[6:9] offset:16384
	s_waitcnt vmcnt(2)
	ds_write_b128 v216, v[10:13] offset:57344
	s_waitcnt vmcnt(1)
	ds_write_b128 v217, v[14:17] offset:57344
	s_waitcnt vmcnt(0)
	ds_write_b128 v218, v[18:21] offset:57344
	v_add_u32_e32 v6, s12, v177
	v_add_u32_e32 v10, s12, v179
	v_add_u32_e32 v11, s12, v181
	v_add_u32_e32 v12, s12, v183
	v_add_u32_e32 v13, s12, v185
	v_add_u32_e32 v14, s12, v187
	v_add_u32_e32 v15, s12, v189
	v_add_u32_e32 v16, s12, v191
	v_add_u32_e32 v17, s12, v193
	v_add_u32_e32 v18, s12, v196
	v_add_u32_e32 v19, s12, v198
	v_add_u32_e32 v20, s12, v213
	s_waitcnt lgkmcnt(0)
	s_barrier
	ds_read_b128 v[2:5], v176 offset:57344
	ds_read_b128 v[6:9], v6
	v_cvt_pk_bf16_f32 v204, v25, v27
	v_cvt_pk_bf16_f32 v205, v28, v29
	v_cvt_pk_bf16_f32 v206, v22, v23
	s_waitcnt lgkmcnt(1)
	v_mfma_f32_32x32x16_bf16 v[82:97], v[2:5], v[128:131], 0
	v_cvt_pk_bf16_f32 v207, v24, v26
	v_permlane32_swap_b32_e32 v204, v206
	s_nop 0
	v_permlane32_swap_b32_e32 v205, v207
	s_waitcnt lgkmcnt(0)
	v_mfma_f32_32x32x16_bf16 v[66:81], v[6:9], v[128:131], 0
	ds_read_b128 v[2:5], v178 offset:57344
	ds_read_b128 v[6:9], v10
	s_waitcnt lgkmcnt(1)
	v_mfma_f32_32x32x16_bf16 v[82:97], v[2:5], v[124:127], v[82:97]
	s_waitcnt lgkmcnt(0)
	v_mfma_f32_32x32x16_bf16 v[66:81], v[6:9], v[124:127], v[66:81]
	ds_read_b128 v[2:5], v180 offset:57344
	ds_read_b128 v[6:9], v11
	s_waitcnt lgkmcnt(1)
	v_mfma_f32_32x32x16_bf16 v[82:97], v[2:5], v[120:123], v[82:97]
	s_waitcnt lgkmcnt(0)
	v_mfma_f32_32x32x16_bf16 v[66:81], v[6:9], v[120:123], v[66:81]
	ds_read_b128 v[2:5], v182 offset:57344
	ds_read_b128 v[6:9], v12
	s_waitcnt lgkmcnt(1)
	v_mfma_f32_32x32x16_bf16 v[82:97], v[2:5], v[116:119], v[82:97]
	s_waitcnt lgkmcnt(0)
	v_mfma_f32_32x32x16_bf16 v[66:81], v[6:9], v[116:119], v[66:81]
	ds_read_b128 v[2:5], v184 offset:57344
	ds_read_b128 v[6:9], v13
	s_waitcnt lgkmcnt(1)
	v_mfma_f32_32x32x16_bf16 v[82:97], v[2:5], v[112:115], v[82:97]
	s_waitcnt lgkmcnt(0)
	v_mfma_f32_32x32x16_bf16 v[66:81], v[6:9], v[112:115], v[66:81]
	ds_read_b128 v[2:5], v186 offset:57344
	ds_read_b128 v[6:9], v14
	v_exp_f32_e32 v14, v39
	s_waitcnt lgkmcnt(1)
	v_mfma_f32_32x32x16_bf16 v[82:97], v[2:5], v[108:111], v[82:97]
	s_waitcnt lgkmcnt(0)
	v_mfma_f32_32x32x16_bf16 v[66:81], v[6:9], v[108:111], v[66:81]
	ds_read_b128 v[2:5], v188 offset:57344
	ds_read_b128 v[6:9], v15
	v_exp_f32_e32 v15, v40
	s_nop 0
	v_cvt_pk_bf16_f32 v224, v14, v15
	s_waitcnt lgkmcnt(1)
	v_mfma_f32_32x32x16_bf16 v[82:97], v[2:5], v[104:107], v[82:97]
	s_waitcnt lgkmcnt(0)
	v_mfma_f32_32x32x16_bf16 v[66:81], v[6:9], v[104:107], v[66:81]
	ds_read_b128 v[2:5], v190 offset:57344
	ds_read_b128 v[6:9], v16
	v_exp_f32_e32 v16, v41
	s_waitcnt lgkmcnt(1)
	v_mfma_f32_32x32x16_bf16 v[82:97], v[2:5], v[100:103], v[82:97]
	s_waitcnt lgkmcnt(0)
	v_mfma_f32_32x32x16_bf16 v[66:81], v[6:9], v[100:103], v[66:81]
	ds_read_b128 v[2:5], v192 offset:57344
	ds_read_b128 v[6:9], v17
	ds_read_b128 v[10:13], v194
	v_exp_f32_e32 v17, v38
	s_nop 0
	v_cvt_pk_bf16_f32 v225, v16, v17
	s_waitcnt lgkmcnt(0)
	v_mfma_f32_32x32x16_bf16 v[82:97], v[2:5], v[10:13], v[82:97]
	v_mfma_f32_32x32x16_bf16 v[66:81], v[6:9], v[10:13], v[66:81]
	ds_read_b128 v[2:5], v195 offset:57344
	ds_read_b128 v[6:9], v18
	ds_read_b128 v[10:13], v172
	v_add_f32_e32 v18, 0, v31
	v_add_f32_e32 v18, v33, v18
	v_add_f32_e32 v18, v34, v18
	v_add_f32_e32 v18, v35, v18
	v_add_f32_e32 v18, v36, v18
	v_add_f32_e32 v18, v37, v18
	s_waitcnt lgkmcnt(0)
	v_mfma_f32_32x32x16_bf16 v[82:97], v[2:5], v[10:13], v[82:97]
	v_add_f32_e32 v18, v30, v18
	v_add_f32_e32 v18, v32, v18
	v_add_f32_e32 v18, v25, v18
	v_add_f32_e32 v18, v27, v18
	v_add_f32_e32 v18, v28, v18
	v_add_f32_e32 v18, v29, v18
	v_add_f32_e32 v18, v22, v18
	v_mfma_f32_32x32x16_bf16 v[66:81], v[6:9], v[10:13], v[66:81]
	ds_read_b128 v[2:5], v197 offset:57344
	ds_read_b128 v[6:9], v19
	ds_read_b128 v[10:13], v173
	v_add_f32_e32 v18, v23, v18
	v_add_f32_e32 v18, v24, v18
	v_add_f32_e32 v18, v26, v18
	s_waitcnt lgkmcnt(0)
	v_mfma_f32_32x32x16_bf16 v[82:97], v[2:5], v[10:13], v[82:97]
	v_mfma_f32_32x32x16_bf16 v[66:81], v[6:9], v[10:13], v[66:81]
	ds_read_b128 v[2:5], v199 offset:57344
	ds_read_b128 v[6:9], v20
	ds_read_b128 v[10:13], v171
	s_waitcnt lgkmcnt(0)
	v_mfma_f32_32x32x16_bf16 v[82:97], v[2:5], v[10:13], v[82:97]
	v_exp_f32_e32 v2, v51
	v_exp_f32_e32 v3, v52
	v_exp_f32_e32 v4, v53
	v_exp_f32_e32 v5, v54
	v_add_f32_e32 v18, v2, v18
	v_add_f32_e32 v18, v3, v18
	v_add_f32_e32 v18, v4, v18
	v_mfma_f32_32x32x16_bf16 v[66:81], v[6:9], v[10:13], v[66:81]
	v_exp_f32_e32 v6, v55
	v_exp_f32_e32 v7, v42
	v_exp_f32_e32 v8, v43
	v_exp_f32_e32 v9, v44
	v_add_f32_e32 v18, v5, v18
	v_exp_f32_e32 v10, v45
	v_add_f32_e32 v18, v6, v18
	v_exp_f32_e32 v11, v47
	v_add_f32_e32 v18, v7, v18
	v_exp_f32_e32 v12, v49
	v_add_f32_e32 v18, v8, v18
	v_exp_f32_e32 v13, v50
	v_add_f32_e32 v18, v9, v18
	v_add_f32_e32 v18, v10, v18
	v_add_f32_e32 v18, v11, v18
	v_add_f32_e32 v18, v12, v18
	v_add_f32_e32 v18, v13, v18
	v_add_f32_e32 v18, v14, v18
	v_add_f32_e32 v18, v15, v18
	v_add_f32_e32 v18, v16, v18
	v_add_f32_e32 v219, v17, v18
	v_mov_b32_e32 v220, v219
	v_cvt_pk_bf16_f32 v50, v31, v33
	v_cvt_pk_bf16_f32 v51, v34, v35
	v_cvt_pk_bf16_f32 v52, v36, v37
	v_cvt_pk_bf16_f32 v53, v30, v32
	v_permlane32_swap_b32_e32 v219, v220
	v_permlane32_swap_b32_e32 v50, v52
	v_permlane32_swap_b32_e32 v51, v53
	v_cvt_pk_bf16_f32 v208, v2, v3
	v_cvt_pk_bf16_f32 v209, v4, v5
	v_cvt_pk_bf16_f32 v210, v6, v7
	v_cvt_pk_bf16_f32 v211, v8, v9
	v_cvt_pk_bf16_f32 v222, v10, v11
	v_cvt_pk_bf16_f32 v223, v12, v13
	v_permlane32_swap_b32_e32 v208, v210
	v_permlane32_swap_b32_e32 v209, v211
	v_permlane32_swap_b32_e32 v222, v224
	v_permlane32_swap_b32_e32 v223, v225
	s_add_u32 s10, s10, 0x1020000
	s_addc_u32 s11, s11, 0
	s_add_u32 s22, s8, 0x1830000
	s_addc_u32 s23, s9, 0
	global_load_dwordx4 v[132:135], v164, s[10:11]
	global_load_dwordx4 v[136:139], v158, s[22:23]
	global_load_dwordx4 v[140:143], v160, s[22:23]
	global_load_dwordx4 v[148:151], v98, s[10:11]
	global_load_dwordx4 v[144:147], v162, s[22:23]
	ds_read_b64_tr_b16 v[2:3], v170 offset:0
	ds_read_b64_tr_b16 v[4:5], v170 offset:0x800
	ds_read_b64_tr_b16 v[18:19], v170 offset:0x1000
	ds_read_b64_tr_b16 v[20:21], v170 offset:0x1800
	ds_read_b64_tr_b16 v[22:23], v170 offset:0x2000
	ds_read_b64_tr_b16 v[24:25], v170 offset:0x2800
	ds_read_b64_tr_b16 v[26:27], v170 offset:0x3000
	ds_read_b64_tr_b16 v[28:29], v170 offset:0x3800
	s_waitcnt lgkmcnt(0)
	s_nop 0
	v_mfma_f32_32x32x16_bf16 v[2:17], v[50:53], v[2:5], 0
	v_mfma_f32_32x32x16_bf16 v[2:17], v[204:207], v[18:21], v[2:17]
	ds_read_b64_tr_b16 v[18:19], v170 offset:0x200
	ds_read_b64_tr_b16 v[20:21], v170 offset:0xa00
	ds_read_b64_tr_b16 v[34:35], v170 offset:0x1200
	ds_read_b64_tr_b16 v[36:37], v170 offset:0x1a00
	ds_read_b64_tr_b16 v[38:39], v170 offset:0x2200
	ds_read_b64_tr_b16 v[40:41], v170 offset:0x2a00
	ds_read_b64_tr_b16 v[42:43], v170 offset:0x3200
	v_mfma_f32_32x32x16_bf16 v[2:17], v[208:211], v[22:25], v[2:17]
	ds_read_b64_tr_b16 v[44:45], v170 offset:0x3a00
	s_waitcnt lgkmcnt(0)
	v_mfma_f32_32x32x16_bf16 v[2:17], v[222:225], v[26:29], v[2:17]
	v_mfma_f32_32x32x16_bf16 v[18:33], v[50:53], v[18:21], 0
	v_mfma_f32_32x32x16_bf16 v[18:33], v[204:207], v[34:37], v[18:33]
	ds_read_b64_tr_b16 v[34:35], v170 offset:0x400
	ds_read_b64_tr_b16 v[36:37], v170 offset:0xc00
	ds_read_b64_tr_b16 v[54:55], v170 offset:0x1400
	ds_read_b64_tr_b16 v[56:57], v170 offset:0x1c00
	ds_read_b64_tr_b16 v[58:59], v170 offset:0x2400
	ds_read_b64_tr_b16 v[60:61], v170 offset:0x2c00
	ds_read_b64_tr_b16 v[62:63], v170 offset:0x3400
	v_mfma_f32_32x32x16_bf16 v[18:33], v[208:211], v[38:41], v[18:33]
	ds_read_b64_tr_b16 v[64:65], v170 offset:0x3c00
	s_waitcnt lgkmcnt(0)
	v_mfma_f32_32x32x16_bf16 v[18:33], v[222:225], v[42:45], v[18:33]
	v_mfma_f32_32x32x16_bf16 v[34:49], v[50:53], v[34:37], 0
	v_mfma_f32_32x32x16_bf16 v[34:49], v[204:207], v[54:57], v[34:49]
	ds_read_b64_tr_b16 v[54:55], v170 offset:0x600
	ds_read_b64_tr_b16 v[56:57], v170 offset:0xe00
	ds_read_b64_tr_b16 v[226:227], v170 offset:0x1600
	ds_read_b64_tr_b16 v[228:229], v170 offset:0x1e00
	ds_read_b64_tr_b16 v[230:231], v170 offset:0x2600
	ds_read_b64_tr_b16 v[232:233], v170 offset:0x2e00
	ds_read_b64_tr_b16 v[234:235], v170 offset:0x3600
	v_mfma_f32_32x32x16_bf16 v[34:49], v[208:211], v[58:61], v[34:49]
	ds_read_b64_tr_b16 v[236:237], v170 offset:0x3e00
	s_waitcnt lgkmcnt(0)
	v_mfma_f32_32x32x16_bf16 v[34:49], v[222:225], v[62:65], v[34:49]
	v_mfma_f32_32x32x16_bf16 v[50:65], v[50:53], v[54:57], 0
	v_max_f32_e32 v155, v83, v83
	v_max_f32_e32 v159, v82, v82
	v_max_f32_e32 v155, v159, v155
	v_max3_f32 v155, v155, v84, v85
	v_max3_f32 v155, v155, v86, v87
	v_max3_f32 v155, v155, v88, v89
	v_max3_f32 v155, v155, v90, v91
	v_mfma_f32_32x32x16_bf16 v[50:65], v[204:207], v[226:229], v[50:65]
	v_max3_f32 v155, v155, v92, v93
	v_max3_f32 v155, v155, v94, v95
	v_max3_f32 v155, v155, v96, v97
	v_max3_f32 v155, v155, v66, v67
	v_max3_f32 v155, v155, v68, v69
	v_max3_f32 v155, v155, v70, v71
	v_max3_f32 v155, v155, v72, v73
	v_max3_f32 v155, v155, v74, v75
	v_mfma_f32_32x32x16_bf16 v[50:65], v[208:211], v[230:233], v[50:65]
	v_max3_f32 v155, v155, v76, v77
	v_max3_f32 v155, v155, v78, v79
	v_max3_f32 v155, v155, v80, v81
	v_mov_b32_e32 v159, v155
	s_nop 1
	v_permlane32_swap_b32_e32 v155, v159
	v_max_f32_e32 v159, v159, v159
	v_max_f32_e32 v155, v155, v155
	v_max_f32_e32 v155, v155, v159
	v_sub_f32_e32 v159, v155, v153
	v_max_f32_e32 v155, v153, v155
	v_mfma_f32_32x32x16_bf16 v[50:65], v[222:225], v[234:237], v[50:65]
	v_cmp_ge_f32_e32 vcc, s5, v159
	v_sub_f32_e32 v159, v153, v155
	v_mul_f32_e32 v159, 0x3dd53b94, v159
	v_exp_f32_e32 v159, v159
	s_cmp_eq_u64 vcc, exec
	s_cselect_b64 s[42:43], -1, 0
	s_barrier
	s_waitcnt vmcnt(0)
	v_cndmask_b32_e64 v221, v159, 1.0, s[42:43]
	v_cmp_gt_f32_e32 vcc, 1.0, v221
	s_waitcnt vmcnt(1)
	ds_write_b128 v214, v[148:151]
	ds_write_b128 v215, v[132:135]
	ds_write_b128 v216, v[136:139] offset:32768
	ds_write_b128 v217, v[140:143] offset:32768
	s_waitcnt vmcnt(0)
	ds_write_b128 v218, v[144:147] offset:32768
	s_cbranch_vccz .LBB0_826
	s_and_saveexec_b64 s[36:37], s[40:41]
	ds_write_b32 v175, v221 offset:128
	s_or_b64 exec, exec, s[36:37]
	s_waitcnt lgkmcnt(0)
	ds_read_b128 v[132:135], v174 offset:224
	ds_read_b128 v[136:139], v174 offset:192
	ds_read_b128 v[140:143], v174 offset:160
	ds_read_b128 v[144:147], v174 offset:128
	s_waitcnt lgkmcnt(3)
	v_pk_mul_f32 v[16:17], v[16:17], v[134:135]
	s_waitcnt lgkmcnt(2)
	v_pk_mul_f32 v[12:13], v[12:13], v[138:139]
	s_waitcnt lgkmcnt(1)
	v_pk_mul_f32 v[8:9], v[8:9], v[142:143]
	s_waitcnt lgkmcnt(0)
	v_pk_mul_f32 v[4:5], v[4:5], v[146:147]
	v_pk_mul_f32 v[14:15], v[14:15], v[132:133]
	v_pk_mul_f32 v[10:11], v[10:11], v[136:137]
	v_pk_mul_f32 v[6:7], v[6:7], v[140:141]
	v_pk_mul_f32 v[2:3], v[2:3], v[144:145]
	v_pk_mul_f32 v[32:33], v[32:33], v[134:135]
	v_pk_mul_f32 v[28:29], v[28:29], v[138:139]
	v_pk_mul_f32 v[24:25], v[24:25], v[142:143]
	v_pk_mul_f32 v[20:21], v[20:21], v[146:147]
	v_pk_mul_f32 v[30:31], v[30:31], v[132:133]
	v_pk_mul_f32 v[26:27], v[26:27], v[136:137]
	v_pk_mul_f32 v[22:23], v[22:23], v[140:141]
	v_pk_mul_f32 v[18:19], v[18:19], v[144:145]
	v_pk_mul_f32 v[48:49], v[48:49], v[134:135]
	v_pk_mul_f32 v[44:45], v[44:45], v[138:139]
	v_pk_mul_f32 v[40:41], v[40:41], v[142:143]
	v_pk_mul_f32 v[36:37], v[36:37], v[146:147]
	v_pk_mul_f32 v[46:47], v[46:47], v[132:133]
	v_pk_mul_f32 v[42:43], v[42:43], v[136:137]
	v_pk_mul_f32 v[38:39], v[38:39], v[140:141]
	v_pk_mul_f32 v[34:35], v[34:35], v[144:145]
	v_pk_mul_f32 v[64:65], v[64:65], v[134:135]
	v_pk_mul_f32 v[60:61], v[60:61], v[138:139]
	v_pk_mul_f32 v[56:57], v[56:57], v[142:143]
	v_pk_mul_f32 v[52:53], v[52:53], v[146:147]
	v_pk_mul_f32 v[62:63], v[62:63], v[132:133]
	v_pk_mul_f32 v[58:59], v[58:59], v[136:137]
	v_pk_mul_f32 v[54:55], v[54:55], v[140:141]
	v_pk_mul_f32 v[50:51], v[50:51], v[144:145]

.LBB0_853:
	s_and_b64 vcc, exec, s[0:1]
	s_cbranch_vccz .LBB0_820
	s_ashr_i32 s14, s49, 5
	s_ashr_i32 s15, s14, 31
	s_lshl_b32 s0, s49, 8
	s_lshl_b64 s[42:43], s[14:15], 11
	s_and_b32 s0, s0, 0x700
	s_or_b32 s42, s42, s0
	s_mul_i32 s0, s43, 0x600
	s_mul_hi_u32 s1, s42, 0x600
	s_bfe_u32 s4, s49, 0x20003
	s_add_i32 s1, s1, s0
	s_mul_i32 s0, s42, 0x600
	s_add_u32 s0, s84, s0
	s_addc_u32 s1, s85, s1
	s_mul_i32 s2, s4, 0x180
	s_add_u32 s16, s0, s2
	s_addc_u32 s17, s1, 0
	v_readlane_b32 s0, v251, 48
	v_readlane_b32 s1, v251, 49
	s_add_u32 s2, s0, s2
	s_addc_u32 s8, s1, 0
	s_lshl_b32 s7, s4, 7
	s_lshl_b32 s0, s4, 8
	v_readlane_b32 s10, v253, 7
	v_mov_b32_e32 v170, v0
	v_readlane_b32 s11, v253, 8
	s_add_u32 s9, s10, s0
	s_addc_u32 s10, s11, 0
	v_ashrrev_i32_e32 v161, 6, v170
	v_and_b32_e32 v172, 31, v170
	v_and_b32_e32 v2, 0x3fffffc0, v170
	s_add_i32 s1, 0, 0x14000
	v_lshlrev_b32_e32 v160, 5, v161
	v_bfe_u32 v173, v170, 5, 1
	v_lshl_add_u32 v64, v2, 2, s1
	v_or_b32_e32 v4, v160, v172
	s_waitcnt lgkmcnt(0)
	v_mov_b64_e32 v[2:3], s[16:17]
	s_movk_i32 s11, 0x600
	v_mad_i64_i32 v[2:3], s[16:17], v4, s11, v[2:3]
	v_lshlrev_b32_e32 v62, 4, v173
	v_mov_b32_e32 v63, v99
	v_lshl_add_u64 v[6:7], v[2:3], 0, v[62:63]
	v_lshlrev_b32_e32 v2, 12, v161
	s_add_i32 s1, 0, 0x14800
	v_lshlrev_b32_e32 v3, 7, v172
	global_load_dwordx4 v[128:131], v[6:7], off
	global_load_dwordx4 v[124:127], v[6:7], off offset:32
	global_load_dwordx4 v[120:123], v[6:7], off offset:64
	global_load_dwordx4 v[116:119], v[6:7], off offset:96
	global_load_dwordx4 v[112:115], v[6:7], off offset:128
	global_load_dwordx4 v[108:111], v[6:7], off offset:160
	global_load_dwordx4 v[104:107], v[6:7], off offset:192
	global_load_dwordx4 v[100:103], v[6:7], off offset:224
	v_add3_u32 v51, s1, v2, v3
	global_load_dwordx4 v[2:5], v[6:7], off offset:256
	global_load_dwordx4 v[132:135], v[6:7], off offset:288
	global_load_dwordx4 v[136:139], v[6:7], off offset:320
	global_load_dwordx4 v[140:143], v[6:7], off offset:352
	v_bitop3_b32 v8, v173, v170, 7 bitop3:0x78
	v_lshl_add_u32 v8, v8, 4, v51
	v_lshlrev_b32_e32 v14, 4, v170
	v_and_b32_e32 v50, 0x70, v14
	s_movk_i32 s1, 0x60
	s_movk_i32 s18, 0x180
	s_lshl_b32 s12, s14, 8
	s_add_i32 s0, s12, 0x4000
	s_lshl_b32 s13, s14, 11
	s_cmp_lg_u32 0, -1
	s_mul_i32 s15, s14, 0x60000
	s_cselect_b32 s14, 0, 0
	v_and_b32_e32 v171, 63, v170
	v_mul_u32_u24_e32 v55, 0x180, v172
	v_or_b32_e32 v52, 32, v62
	v_bitop3_b32 v56, v52, v55, v50 bitop3:0xde
	v_add_u32_e32 v184, 0, v56
	v_or_b32_e32 v53, 64, v62
	v_or_b32_e32 v54, 0x60, v62
	s_mov_b32 s68, s69
	s_mov_b32 s70, s69
	s_mov_b32 s71, s69
	s_mov_b32 s72, s69
	s_mov_b32 s73, s69
	s_mov_b32 s74, s69
	s_mov_b32 s75, s69
	s_mov_b32 s76, s69
	s_mov_b32 s77, s69
	s_mov_b32 s78, s69
	s_mov_b32 s79, s69
	s_mov_b32 s80, s69
	s_mov_b32 s81, s69
	s_mov_b32 s82, s69
	s_mov_b32 s83, s69
	v_lshl_add_u32 v197, v172, 2, v64
	v_add_u32_e32 v193, v64, v62
	v_mov_b32_e32 v212, 0x358637bd
	v_mov_b32_e32 v200, 0xff
	v_mov_b32_e32 v202, 0x1b00
	v_mov_b32_e32 v201, 0x600
	v_mov_b32_e32 v203, 0x260
	v_mov_b32_e32 v169, v99
	v_mov_b32_e32 v163, v99
	v_mov_b32_e32 v165, v99
	v_mov_b32_e32 v167, v99
	v_cmp_gt_u32_e64 s[38:39], 32, v171
	v_mov_b32_e32 v198, 0
	s_waitcnt vmcnt(0)
	ds_write_b128 v8, v[2:5]
	v_bitop3_b32 v8, v62, v50, 32 bitop3:0x36
	v_add_u32_e32 v176, v51, v8
	v_bitop3_b32 v8, v62, v50, 64 bitop3:0x36
	v_add_u32_e32 v177, v51, v8
	ds_write_b128 v176, v[132:135]
	ds_write_b128 v177, v[136:139]
	v_bitop3_b32 v6, v62, v50, s1 bitop3:0x36
	v_add_u32_e32 v175, v51, v6
	s_mov_b32 s1, 0x2aaaaaab
	ds_write_b128 v175, v[140:143]
	v_ashrrev_i32_e32 v2, 4, v170
	v_and_b32_e32 v5, 0xfffff0, v2
	v_lshlrev_b32_e32 v6, 1, v2
	v_and_or_b32 v5, v6, 8, v5
	v_lshrrev_b32_e32 v6, 1, v2
	v_and_b32_e32 v7, 3, v2
	v_and_or_b32 v6, v6, 4, v7
	v_add_u32_e32 v7, 32, v2
	v_and_b32_e32 v8, 0xfffff0, v7
	v_lshlrev_b32_e32 v7, 1, v7
	v_lshlrev_b32_e32 v3, 3, v170
	v_and_or_b32 v7, v7, 8, v8
	v_and_b32_e32 v4, 0x78, v3
	v_lshrrev_b32_e32 v5, 1, v5
	v_bfe_u32 v3, v3, 5, 2
	v_lshrrev_b32_e32 v7, 1, v7
	v_or_b32_e32 v5, v5, v3
	v_or_b32_e32 v3, v7, v3
	v_mul_hi_i32 v7, v170, s1
	v_lshrrev_b32_e32 v8, 31, v7
	v_ashrrev_i32_e32 v7, 2, v7
	v_add_u32_e32 v7, v7, v8
	v_mul_lo_u32 v8, v7, 24
	v_sub_u32_e32 v8, v170, v8
	v_mul_lo_u32 v9, v7, s11
	v_lshl_add_u32 v162, v8, 4, v9
	v_mul_lo_u32 v9, v7, s18
	v_bitop3_b32 v7, v7, v8, 7 bitop3:0x6c
	v_lshl_add_u32 v15, v7, 4, v9
	v_add_u32_e32 v7, 0x200, v170
	v_mul_hi_i32 v8, v7, s1
	v_lshrrev_b32_e32 v9, 31, v8
	v_ashrrev_i32_e32 v8, 2, v8
	v_add_u32_e32 v8, v8, v9
	v_mul_lo_u32 v9, v8, 24
	v_sub_u32_e32 v7, v7, v9
	v_mul_lo_u32 v9, v8, s11
	v_lshl_add_u32 v164, v7, 4, v9
	v_mul_lo_u32 v9, v8, s18
	v_bitop3_b32 v7, v8, v7, 7 bitop3:0x6c
	v_lshl_add_u32 v24, v7, 4, v9
	v_add_u32_e32 v7, 0x400, v170
	v_mul_hi_i32 v8, v7, s1
	v_lshrrev_b32_e32 v9, 31, v8
	v_ashrrev_i32_e32 v8, 2, v8
	v_add_u32_e32 v8, v8, v9
	v_mul_lo_u32 v9, v8, 24
	v_sub_u32_e32 v7, v7, v9
	v_mul_lo_u32 v9, v8, s11
	v_lshlrev_b32_e32 v4, 1, v4
	v_lshl_add_u32 v166, v7, 4, v9
	v_mul_lo_u32 v9, v8, s18
	v_bitop3_b32 v7, v8, v7, 7 bitop3:0x6c
	s_ashr_i32 s1, s0, 31
	v_lshlrev_b32_e32 v6, 6, v6
	v_lshlrev_b32_e32 v3, 9, v3
	v_lshl_add_u32 v25, v7, 4, v9
	v_and_b32_e32 v7, 48, v4
	s_lshl_b64 s[16:17], s[0:1], 10
	v_or3_b32 v27, v3, v6, v7
	v_lshl_or_b32 v98, v2, 10, v4
	v_lshlrev_b32_e32 v2, 3, v171
	v_and_b32_e32 v3, 0xc0, v14
	v_lshlrev_b32_e32 v4, 1, v170
	s_add_u32 s16, s9, s16
	v_lshlrev_b32_e32 v5, 9, v5
	v_and_or_b32 v3, v2, 24, v3
	v_and_b32_e32 v4, 32, v4
	v_and_b32_e32 v2, 0x100, v2
	s_addc_u32 s17, s10, s17
	v_or3_b32 v26, v5, v6, v7
	v_or3_b32 v63, v3, v4, v2
	s_add_i32 s15, s15, 0x1800000
	global_load_dwordx4 v[2:5], v98, s[16:17]
	s_mul_hi_i32 s1, s0, 0x600
	s_add_u32 s0, s2, s15
	v_add_u32_e32 v168, 0x8000, v98
	s_addc_u32 s1, s8, s1
	global_load_dwordx4 v[6:9], v168, s[16:17]
	global_load_dwordx4 v[10:13], v162, s[0:1]
	global_load_dwordx4 v[16:19], v164, s[0:1]
	global_load_dwordx4 v[20:23], v166, s[0:1]
	v_add_u32_e32 v178, 0, v26
	s_waitcnt vmcnt(0)
	v_add_u32_e32 v179, 0, v27
	v_add_u32_e32 v180, 0, v15
	v_add_u32_e32 v181, 0, v24
	v_add_u32_e32 v182, 0, v25
	s_movk_i32 s0, 0x70
	v_bitop3_b32 v61, v62, v14, s0 bitop3:0x78
	s_movk_i32 s0, 0x80
	v_add_u32_e32 v192, v51, v61
	v_add_u32_e32 v174, s14, v63
	s_mov_b32 s11, -1
	s_waitcnt vmcnt(4)
	ds_write_b128 v178, v[2:5]
	v_mov_b32_e32 v2, 0x3000
	v_mad_u32_u24 v60, v172, s18, v2
	v_bitop3_b32 v2, v62, v55, v50 bitop3:0xde
	v_add_u32_e32 v183, 0, v2
	s_waitcnt vmcnt(3)
	ds_write_b128 v179, v[6:9]
	s_waitcnt vmcnt(2)
	ds_write_b128 v180, v[10:13] offset:32768
	s_waitcnt vmcnt(1)
	ds_write_b128 v181, v[16:19] offset:32768
	s_waitcnt vmcnt(0)
	ds_write_b128 v182, v[20:23] offset:32768
	s_waitcnt lgkmcnt(0)
	s_barrier
	ds_read_b128 v[18:21], v183 offset:32768
	ds_read_b128 v[22:25], v183 offset:45056
	ds_read_b128 v[56:59], v184 offset:32768
	ds_read_b128 v[68:71], v184 offset:45056
	s_waitcnt lgkmcnt(3)
	v_mfma_f32_32x32x16_bf16 v[34:49], v[18:21], v[128:131], 0
	v_bitop3_b32 v66, v52, v60, v50 bitop3:0xde
	v_bitop3_b32 v52, v53, v55, v50 bitop3:0xde
	v_add_u32_e32 v185, 0, v52
	v_bitop3_b32 v52, v54, v55, v50 bitop3:0xde
	v_add_u32_e32 v186, 0, v52
	v_bitop3_b32 v67, v53, v60, v50 bitop3:0xde
	v_mov_b64_e32 v[2:3], s[68:69]
	s_waitcnt lgkmcnt(2)
	v_mfma_f32_32x32x16_bf16 v[18:33], v[22:25], v[128:131], 0
	v_mov_b64_e32 v[4:5], s[70:71]
	v_mov_b64_e32 v[6:7], s[72:73]
	v_mov_b64_e32 v[8:9], s[74:75]
	v_mov_b64_e32 v[10:11], s[76:77]
	v_mov_b64_e32 v[12:13], s[78:79]
	v_mov_b64_e32 v[14:15], s[80:81]
	v_mov_b64_e32 v[16:17], s[82:83]
	s_waitcnt lgkmcnt(1)
	v_mfma_f32_32x32x16_bf16 v[34:49], v[56:59], v[124:127], v[34:49]
	ds_read_b128 v[56:59], v185 offset:32768
	s_movk_i32 s82, 0x100
	ds_read_b128 v[74:77], v192
	v_bitop3_b32 v65, v62, v60, v50 bitop3:0xde
	v_readlane_b32 s80, v254, 41
	v_readlane_b32 s74, v254, 44
	v_readlane_b32 s81, v254, 42
	s_waitcnt lgkmcnt(2)
	v_mfma_f32_32x32x16_bf16 v[18:33], v[68:71], v[124:127], v[18:33]
	ds_read_b128 v[68:71], v185 offset:45056
	v_add_u32_e32 v226, 0, v65
	v_readlane_b32 s75, v254, 45
	v_readlane_b32 s83, v254, 43
	s_movk_i32 s81, 0x300
	v_add_u32_e32 v225, 0, v66
	v_add_u32_e32 v224, 0, v67
	s_waitcnt lgkmcnt(2)
	v_mfma_f32_32x32x16_bf16 v[34:49], v[56:59], v[120:123], v[34:49]
	ds_read_b128 v[56:59], v186 offset:32768
	s_waitcnt lgkmcnt(1)
	v_mfma_f32_32x32x16_bf16 v[18:33], v[68:71], v[120:123], v[18:33]
	v_bitop3_b32 v68, v54, v60, v50 bitop3:0xde
	ds_read_b128 v[52:55], v186 offset:45056
	v_add_u32_e32 v223, 0, v68
	s_waitcnt lgkmcnt(1)
	v_mfma_f32_32x32x16_bf16 v[34:49], v[56:59], v[116:119], v[34:49]
	v_bitop3_b32 v56, v62, v50, s0 bitop3:0x36
	v_add_u32_e32 v69, v56, v60
	s_movk_i32 s0, 0xa0
	v_add_u32_e32 v222, 0, v69
	s_waitcnt lgkmcnt(0)
	v_mfma_f32_32x32x16_bf16 v[18:33], v[52:55], v[116:119], v[18:33]
	v_mad_u32_u24 v52, v172, s18, v56
	v_add_u32_e32 v187, 0, v52
	ds_read_b128 v[52:55], v187 offset:32768
	ds_read_b128 v[56:59], v187 offset:45056
	s_waitcnt lgkmcnt(0)
	v_mfma_f32_32x32x16_bf16 v[18:33], v[56:59], v[112:115], v[18:33]
	v_bitop3_b32 v56, v62, v50, s0 bitop3:0x36
	v_add_u32_e32 v70, v56, v60
	s_movk_i32 s0, 0xc0
	v_add_u32_e32 v221, 0, v70
	v_mfma_f32_32x32x16_bf16 v[34:49], v[52:55], v[112:115], v[34:49]
	v_mad_u32_u24 v52, v172, s18, v56
	v_add_u32_e32 v188, 0, v52
	ds_read_b128 v[52:55], v188 offset:32768
	ds_read_b128 v[56:59], v188 offset:45056
	s_waitcnt lgkmcnt(0)
	v_mfma_f32_32x32x16_bf16 v[18:33], v[56:59], v[108:111], v[18:33]
	v_bitop3_b32 v56, v62, v50, s0 bitop3:0x36
	v_add_u32_e32 v71, v56, v60
	s_movk_i32 s0, 0xe0
	v_add_u32_e32 v220, 0, v71
	v_mfma_f32_32x32x16_bf16 v[34:49], v[52:55], v[108:111], v[34:49]
	v_mad_u32_u24 v52, v172, s18, v56
	v_add_u32_e32 v189, 0, v52
	ds_read_b128 v[52:55], v189 offset:32768
	ds_read_b128 v[56:59], v189 offset:45056
	s_waitcnt lgkmcnt(0)
	v_mfma_f32_32x32x16_bf16 v[18:33], v[56:59], v[104:107], v[18:33]
	v_bitop3_b32 v56, v62, v50, s0 bitop3:0x36
	v_add_u32_e32 v72, v56, v60
	s_movk_i32 s0, 0x120
	v_bitop3_b32 v51, v62, v50, s0 bitop3:0x36
	s_movk_i32 s0, 0x140
	v_add_u32_e32 v219, 0, v72
	v_mfma_f32_32x32x16_bf16 v[34:49], v[52:55], v[104:107], v[34:49]
	v_mad_u32_u24 v52, v172, s18, v56
	v_add_u32_e32 v190, 0, v52
	ds_read_b128 v[52:55], v190 offset:32768
	ds_read_b128 v[56:59], v190 offset:45056
	s_waitcnt lgkmcnt(0)
	v_mfma_f32_32x32x16_bf16 v[18:33], v[56:59], v[100:103], v[18:33]
	v_bitop3_b32 v56, v62, v50, s82 bitop3:0x36
	v_add_u32_e32 v73, v56, v60
	v_add_u32_e32 v218, 0, v73
	v_mfma_f32_32x32x16_bf16 v[34:49], v[52:55], v[100:103], v[34:49]
	v_mad_u32_u24 v52, v172, s18, v56
	v_add_u32_e32 v191, 0, v52
	ds_read_b128 v[52:55], v191 offset:32768
	ds_read_b128 v[56:59], v191 offset:45056
	s_waitcnt lgkmcnt(1)
	v_mfma_f32_32x32x16_bf16 v[34:49], v[52:55], v[74:77], v[34:49]
	v_mad_u32_u24 v52, v172, s18, v51
	v_add_u32_e32 v194, 0, v52
	ds_read_b128 v[52:55], v194 offset:32768
	s_waitcnt lgkmcnt(1)
	v_mfma_f32_32x32x16_bf16 v[18:33], v[56:59], v[74:77], v[18:33]
	ds_read_b128 v[56:59], v194 offset:45056
	ds_read_b128 v[76:79], v176
	v_add_u32_e32 v74, v51, v60
	v_bitop3_b32 v51, v62, v50, s0 bitop3:0x36
	s_movk_i32 s0, 0x160
	v_bitop3_b32 v50, v62, v50, s0 bitop3:0x36
	v_add_u32_e32 v75, v51, v60
	v_add_u32_e32 v217, 0, v74
	s_waitcnt lgkmcnt(0)
	v_mfma_f32_32x32x16_bf16 v[34:49], v[52:55], v[76:79], v[34:49]
	v_mad_u32_u24 v52, v172, s18, v51
	v_add_u32_e32 v195, 0, v52
	ds_read_b128 v[52:55], v195 offset:32768
	v_mad_u32_u24 v51, v172, s18, v50
	v_add_u32_e32 v196, 0, v51
	v_add_u32_e32 v216, 0, v75
	v_mfma_f32_32x32x16_bf16 v[18:33], v[56:59], v[76:79], v[18:33]
	ds_read_b128 v[56:59], v195 offset:45056
	ds_read_b128 v[76:79], v177
	s_waitcnt lgkmcnt(0)
	v_mfma_f32_32x32x16_bf16 v[34:49], v[52:55], v[76:79], v[34:49]
	v_mfma_f32_32x32x16_bf16 v[18:33], v[56:59], v[76:79], v[18:33]
	ds_read_b128 v[54:57], v196 offset:32768
	v_add_u32_e32 v76, v50, v60
	ds_read_b128 v[50:53], v196 offset:45056
	ds_read_b128 v[58:61], v175
	v_add_u32_e32 v215, 0, v76
	s_waitcnt lgkmcnt(0)
	v_mfma_f32_32x32x16_bf16 v[34:49], v[54:57], v[58:61], v[34:49]
	v_mfma_f32_32x32x16_bf16 v[18:33], v[50:53], v[58:61], v[18:33]
	s_nop 10
	v_max_f32_e32 v50, v35, v35
	v_max_f32_e32 v51, v34, v34
	v_max_f32_e32 v50, v51, v50
	v_max3_f32 v50, v50, v36, v37
	v_max3_f32 v50, v50, v38, v39
	v_max3_f32 v50, v50, v40, v41
	v_max3_f32 v50, v50, v42, v43
	v_max3_f32 v50, v50, v44, v45
	v_max3_f32 v50, v50, v46, v47
	v_max3_f32 v50, v50, v48, v49
	v_max3_f32 v50, v50, v18, v19
	v_max3_f32 v50, v50, v20, v21
	v_max3_f32 v50, v50, v22, v23
	v_max3_f32 v50, v50, v24, v25
	v_max3_f32 v50, v50, v26, v27
	v_max3_f32 v50, v50, v28, v29
	v_max3_f32 v50, v50, v30, v31
	v_max3_f32 v50, v50, v32, v33
	v_mov_b32_e32 v51, v50
	s_nop 1
	v_permlane32_swap_b32_e32 v50, v51
	v_max_f32_e32 v51, v51, v51
	v_max_f32_e32 v50, v50, v50
	v_max_f32_e32 v50, v50, v51
	v_add_f32_e32 v51, 0x7149f2ca, v50
	v_max_f32_e32 v50, 0xf149f2ca, v50
	v_cmp_ge_f32_e32 vcc, s5, v51
	v_sub_f32_e32 v51, 0xf149f2ca, v50
	s_cmp_eq_u64 vcc, exec
	v_mul_f32_e32 v51, 0x3dd53b94, v51
	s_cselect_b64 vcc, -1, 0
	v_exp_f32_e32 v51, v51
	s_add_i32 s0, s12, 0x4040
	v_mov_b32_e32 v52, 0xf149f2ca
	s_ashr_i32 s1, s0, 31
	v_cndmask_b32_e32 v214, v50, v52, vcc
	s_lshl_b64 s[16:17], s[0:1], 10
	v_mul_f32_e32 v50, 0xbdd53b94, v214
	s_add_u32 s16, s9, s16
	v_cndmask_b32_e64 v213, v51, 1.0, vcc
	v_mov_b32_e32 v51, v50
	s_addc_u32 s17, s10, s17
	s_mul_hi_i32 s1, s0, 0x600
	s_mulk_i32 s0, 0x600
	v_fmamk_f32 v34, v34, 0x3dd53b94, v50
	v_fmamk_f32 v35, v35, 0x3dd53b94, v50
	v_fmamk_f32 v36, v36, 0x3dd53b94, v50
	v_fmamk_f32 v37, v37, 0x3dd53b94, v50
	v_fmac_f32_e32 v51, 0x3dd53b94, v49
	s_add_u32 s0, s2, s0
	v_pk_fma_f32 v[138:139], v[32:33], s[30:31], v[50:51] op_sel_hi:[1,0,0]
	v_pk_fma_f32 v[140:141], v[30:31], s[30:31], v[50:51] op_sel_hi:[1,0,0]
	v_pk_fma_f32 v[146:147], v[28:29], s[30:31], v[50:51] op_sel_hi:[1,0,0]
	v_pk_fma_f32 v[132:133], v[26:27], s[30:31], v[50:51] op_sel_hi:[1,0,0]
	v_pk_fma_f32 v[134:135], v[24:25], s[30:31], v[50:51] op_sel_hi:[1,0,0]
	v_pk_fma_f32 v[136:137], v[22:23], s[30:31], v[50:51] op_sel_hi:[1,0,0]
	v_pk_fma_f32 v[142:143], v[20:21], s[30:31], v[50:51] op_sel_hi:[1,0,0]
	v_pk_fma_f32 v[144:145], v[18:19], s[30:31], v[50:51] op_sel_hi:[1,0,0]
	v_exp_f32_e32 v153, v34
	v_exp_f32_e32 v154, v35
	v_exp_f32_e32 v230, v36
	v_exp_f32_e32 v231, v37
	s_addc_u32 s1, s8, s1
	global_load_dwordx4 v[18:21], v98, s[16:17]
	global_load_dwordx4 v[22:25], v168, s[16:17]
	global_load_dwordx4 v[26:29], v162, s[0:1]
	global_load_dwordx4 v[30:33], v164, s[0:1]
	global_load_dwordx4 v[34:37], v166, s[0:1]
	v_fmamk_f32 v38, v38, 0x3dd53b94, v50
	v_fmamk_f32 v39, v39, 0x3dd53b94, v50
	v_fmamk_f32 v40, v40, 0x3dd53b94, v50
	v_fmamk_f32 v41, v41, 0x3dd53b94, v50
	v_fmamk_f32 v42, v42, 0x3dd53b94, v50
	v_fmamk_f32 v43, v43, 0x3dd53b94, v50
	v_fmamk_f32 v44, v44, 0x3dd53b94, v50
	v_fmamk_f32 v45, v45, 0x3dd53b94, v50
	v_fmamk_f32 v46, v46, 0x3dd53b94, v50
	v_fmamk_f32 v47, v47, 0x3dd53b94, v50
	v_fmamk_f32 v48, v48, 0x3dd53b94, v50
	v_exp_f32_e32 v232, v38
	v_exp_f32_e32 v233, v39
	v_exp_f32_e32 v155, v40
	v_exp_f32_e32 v229, v41
	v_exp_f32_e32 v151, v42
	v_exp_f32_e32 v156, v43
	v_exp_f32_e32 v157, v44
	v_exp_f32_e32 v158, v45
	v_exp_f32_e32 v148, v46
	v_exp_f32_e32 v149, v47
	v_exp_f32_e32 v150, v48
	v_exp_f32_e32 v159, v51
	s_waitcnt vmcnt(0)
	s_addk_i32 s14, 0x4000
	s_waitcnt vmcnt(4)
	ds_write_b128 v178, v[18:21] offset:16384
	s_waitcnt vmcnt(3)
	ds_write_b128 v179, v[22:25] offset:16384
	s_waitcnt vmcnt(2)
	ds_write_b128 v180, v[26:29] offset:57344
	s_waitcnt vmcnt(1)
	ds_write_b128 v181, v[30:33] offset:57344
	s_waitcnt vmcnt(0)
	ds_write_b128 v182, v[34:37] offset:57344
	v_add_u32_e32 v199, s14, v63
	v_mov_b64_e32 v[64:65], v[16:17]
	v_mov_b64_e32 v[48:49], v[16:17]
	v_mov_b64_e32 v[32:33], v[16:17]
	s_addk_i32 s12, 0x4080
	s_sub_i32 s13, s13, 64
	v_mov_b64_e32 v[62:63], v[14:15]
	v_mov_b64_e32 v[60:61], v[12:13]
	v_mov_b64_e32 v[58:59], v[10:11]
	v_mov_b64_e32 v[56:57], v[8:9]
	v_mov_b64_e32 v[54:55], v[6:7]
	v_mov_b64_e32 v[52:53], v[4:5]
	v_mov_b64_e32 v[50:51], v[2:3]
	v_mov_b64_e32 v[46:47], v[14:15]
	v_mov_b64_e32 v[44:45], v[12:13]
	v_mov_b64_e32 v[42:43], v[10:11]
	v_mov_b64_e32 v[40:41], v[8:9]
	v_mov_b64_e32 v[38:39], v[6:7]
	v_mov_b64_e32 v[36:37], v[4:5]
	v_mov_b64_e32 v[34:35], v[2:3]
	v_mov_b64_e32 v[30:31], v[14:15]
	v_mov_b64_e32 v[28:29], v[12:13]
	v_mov_b64_e32 v[26:27], v[10:11]
	v_mov_b64_e32 v[24:25], v[8:9]
	v_mov_b64_e32 v[22:23], v[6:7]
	v_mov_b64_e32 v[20:21], v[4:5]
	v_mov_b64_e32 v[18:19], v[2:3]
	s_waitcnt lgkmcnt(0)
	s_barrier
